# GEMM tiles: accumulators initialised by first k-step MFMAs with srcC=0 instead of 128 v_mov per tile (on v10 base)
# baseline (speedup 1.0000x reference)
.LBB0_178:
	s_or_b64 exec, exec, s[10:11]
	v_readlane_b32 s12, v250, 9
	v_readlane_b32 s14, v250, 11
	v_readlane_b32 s15, v250, 12
	s_add_u32 s8, s14, s8
	s_addc_u32 s9, s15, s9
	s_add_u32 s10, s14, s0
	s_addc_u32 s11, s15, s1
	s_mov_b32 s3, 0
	v_add_u32_e32 v176, 0x18000, v174
	v_readlane_b32 s13, v250, 10
	s_add_u32 s18, s8, 0x5800080
	s_addc_u32 s19, s9, 0
	s_add_u32 s20, s18, 0x20000
	s_addc_u32 s21, s19, 0
	s_add_u32 s22, s18, 0x40000
	s_addc_u32 s23, s19, 0
	s_add_u32 s24, s18, 0x60000
	s_addc_u32 s25, s19, 0
	s_add_u32 s8, s10, 0x5100080
	s_addc_u32 s9, s11, 0
	s_add_u32 s10, s8, 0x20000
	s_addc_u32 s11, s9, 0
	s_add_u32 s12, s8, 0x40000
	s_addc_u32 s13, s9, 0
	s_add_u32 s14, s8, 0x60000
	s_addc_u32 s15, s9, 0
	v_lshrrev_b32_e32 v170, 3, v204
	v_lshrrev_b32_e32 v171, 4, v204
	v_xor_b32_e32 v171, v171, v204
	v_and_b32_e32 v171, 7, v171
	v_lshlrev_b32_e32 v171, 4, v171
	v_lshl_or_b32 v170, v170, 11, v171
	v_readfirstlane_b32 s26, v204
	s_and_b32 s26, s26, 0x3c0
	s_lshl_b32 s26, s26, 4
	s_mov_b32 s3, 0
	ds_read_b128 v[130:133], v225
	ds_read_b128 v[138:141], v226
	ds_read_b128 v[134:137], v225 offset:4096
	ds_read_b128 v[142:145], v226 offset:4096
	ds_read_b128 v[146:149], v226 offset:8192
	ds_read_b128 v[150:153], v226 offset:12288
	s_add_u32 m0, s26, 0x8000
	s_nop 0
	global_load_lds_dwordx4 v170, s[8:9]
	s_add_u32 m0, s26, 0x18000
	s_nop 0
	global_load_lds_dwordx4 v170, s[18:19]
	s_add_u32 m0, s26, 0xa000
	s_nop 0
	global_load_lds_dwordx4 v170, s[10:11]
	s_add_u32 m0, s26, 0x1a000
	s_nop 0
	global_load_lds_dwordx4 v170, s[20:21]
	s_add_u32 m0, s26, 0xc000
	s_nop 0
	global_load_lds_dwordx4 v170, s[12:13]
	s_add_u32 m0, s26, 0x1c000
	s_nop 0
	global_load_lds_dwordx4 v170, s[22:23]
	s_add_u32 m0, s26, 0xe000
	s_nop 0
	global_load_lds_dwordx4 v170, s[14:15]
	s_add_u32 m0, s26, 0x1e000
	s_nop 0
	global_load_lds_dwordx4 v170, s[24:25]
	ds_read_b128 v[154:157], v227
	ds_read_b128 v[162:165], v228
	ds_read_b128 v[158:161], v227 offset:4096
	ds_read_b128 v[166:169], v228 offset:4096
	ds_read_b128 v[178:181], v228 offset:8192
	ds_read_b128 v[182:185], v228 offset:12288
	s_waitcnt lgkmcnt(6)
	v_mfma_f32_32x32x16_bf16 v[98:113], v[130:133], v[138:141], 0
	s_add_u32 s8, s8, 0x80
	s_addc_u32 s9, s9, 0
	v_mfma_f32_32x32x16_bf16 v[114:129], v[134:137], v[138:141], 0
	s_add_u32 s10, s10, 0x80
	s_addc_u32 s11, s11, 0
	v_mfma_f32_32x32x16_bf16 v[66:81], v[130:133], v[142:145], 0
	s_add_u32 s12, s12, 0x80
	s_addc_u32 s13, s13, 0
	v_mfma_f32_32x32x16_bf16 v[82:97], v[134:137], v[142:145], 0
	s_add_u32 s14, s14, 0x80
	s_addc_u32 s15, s15, 0
	v_mfma_f32_32x32x16_bf16 v[34:49], v[130:133], v[146:149], 0
	s_add_u32 s18, s18, 0x80
	s_addc_u32 s19, s19, 0
	v_mfma_f32_32x32x16_bf16 v[50:65], v[134:137], v[146:149], 0
	s_add_u32 s20, s20, 0x80
	s_addc_u32 s21, s21, 0
	v_mfma_f32_32x32x16_bf16 v[2:17], v[130:133], v[150:153], 0
	s_add_u32 s22, s22, 0x80
	s_addc_u32 s23, s23, 0
	v_mfma_f32_32x32x16_bf16 v[18:33], v[134:137], v[150:153], 0
	s_add_u32 s24, s24, 0x80
	s_addc_u32 s25, s25, 0
	s_branch .Lg_cin_mid2

.Lg_cin_mid2:
	ds_read_b128 v[130:133], v229
	ds_read_b128 v[138:141], v230
	ds_read_b128 v[134:137], v229 offset:4096
	ds_read_b128 v[142:145], v230 offset:4096
	ds_read_b128 v[146:149], v230 offset:8192
	ds_read_b128 v[150:153], v230 offset:12288
	s_waitcnt lgkmcnt(6)
	v_mfma_f32_32x32x16_bf16 v[98:113], v[154:157], v[162:165], v[98:113]
	v_mfma_f32_32x32x16_bf16 v[114:129], v[158:161], v[162:165], v[114:129]
	v_mfma_f32_32x32x16_bf16 v[66:81], v[154:157], v[166:169], v[66:81]
	v_mfma_f32_32x32x16_bf16 v[82:97], v[158:161], v[166:169], v[82:97]
	v_mfma_f32_32x32x16_bf16 v[34:49], v[154:157], v[178:181], v[34:49]
	v_mfma_f32_32x32x16_bf16 v[50:65], v[158:161], v[178:181], v[50:65]
	v_mfma_f32_32x32x16_bf16 v[2:17], v[154:157], v[182:185], v[2:17]
	v_mfma_f32_32x32x16_bf16 v[18:33], v[158:161], v[182:185], v[18:33]
	ds_read_b128 v[154:157], v231
	ds_read_b128 v[162:165], v232
	ds_read_b128 v[158:161], v231 offset:4096
	ds_read_b128 v[166:169], v232 offset:4096
	ds_read_b128 v[178:181], v232 offset:8192
	ds_read_b128 v[182:185], v232 offset:12288
	s_waitcnt lgkmcnt(6)
	v_mfma_f32_32x32x16_bf16 v[98:113], v[130:133], v[138:141], v[98:113]
	v_mfma_f32_32x32x16_bf16 v[114:129], v[134:137], v[138:141], v[114:129]
	v_mfma_f32_32x32x16_bf16 v[66:81], v[130:133], v[142:145], v[66:81]
	v_mfma_f32_32x32x16_bf16 v[82:97], v[134:137], v[142:145], v[82:97]
	v_mfma_f32_32x32x16_bf16 v[34:49], v[130:133], v[146:149], v[34:49]
	v_mfma_f32_32x32x16_bf16 v[50:65], v[134:137], v[146:149], v[50:65]
	v_mfma_f32_32x32x16_bf16 v[2:17], v[130:133], v[150:153], v[2:17]
	v_mfma_f32_32x32x16_bf16 v[18:33], v[134:137], v[150:153], v[18:33]
	s_waitcnt vmcnt(0) lgkmcnt(0)
	s_barrier
	ds_read_b128 v[130:133], v225 offset:32768
	ds_read_b128 v[138:141], v234
	ds_read_b128 v[134:137], v225 offset:36864
	ds_read_b128 v[142:145], v234 offset:4096
	ds_read_b128 v[146:149], v234 offset:8192
	ds_read_b128 v[150:153], v234 offset:12288
	s_cmp_ge_u32 s3, 14
	s_cbranch_scc1 .Lg_cin_nodma
	s_add_u32 m0, s26, 0x0
	v_mfma_f32_32x32x16_bf16 v[98:113], v[154:157], v[162:165], v[98:113]
	global_load_lds_dwordx4 v170, s[8:9]
	s_add_u32 m0, s26, 0x10000
	v_mfma_f32_32x32x16_bf16 v[114:129], v[158:161], v[162:165], v[114:129]
	global_load_lds_dwordx4 v170, s[18:19]
	s_add_u32 m0, s26, 0x2000
	v_mfma_f32_32x32x16_bf16 v[66:81], v[154:157], v[166:169], v[66:81]
	global_load_lds_dwordx4 v170, s[10:11]
	s_add_u32 m0, s26, 0x12000
	v_mfma_f32_32x32x16_bf16 v[82:97], v[158:161], v[166:169], v[82:97]
	global_load_lds_dwordx4 v170, s[20:21]
	s_add_u32 m0, s26, 0x4000
	v_mfma_f32_32x32x16_bf16 v[34:49], v[154:157], v[178:181], v[34:49]
	global_load_lds_dwordx4 v170, s[12:13]
	s_add_u32 m0, s26, 0x14000
	v_mfma_f32_32x32x16_bf16 v[50:65], v[158:161], v[178:181], v[50:65]
	global_load_lds_dwordx4 v170, s[22:23]
	s_add_u32 m0, s26, 0x6000
	v_mfma_f32_32x32x16_bf16 v[2:17], v[154:157], v[182:185], v[2:17]
	global_load_lds_dwordx4 v170, s[14:15]
	s_add_u32 m0, s26, 0x16000
	v_mfma_f32_32x32x16_bf16 v[18:33], v[158:161], v[182:185], v[18:33]
	global_load_lds_dwordx4 v170, s[24:25]
	s_branch .Lg_cin_join

.LBB0_1123:
	s_bfe_u32 s4, s14, 0x20003
	s_lshr_b32 s0, s14, 5
	s_lshl_b32 s0, s0, 3
	s_and_b32 s1, s14, 7
	s_add_i32 s0, s0, s1
	s_lshl_b32 s2, s0, 8
	s_ashr_i32 s3, s2, 31
	s_ashr_i32 s5, s4, 31
	s_lshl_b64 s[0:1], s[4:5], 19
	s_lshl_b64 s[6:7], s[2:3], 11
	v_readlane_b32 s8, v252, 31
	v_readlane_b32 s9, v252, 32
	s_add_u32 s8, s8, s6
	v_mov_b32_e32 v34, v178
	s_addc_u32 s9, s9, s7
	v_readlane_b32 s3, v252, 49
	s_add_u32 s10, s3, s0
	v_lshlrev_b32_e32 v0, 4, v34
	v_readlane_b32 s3, v252, 50
	v_ashrrev_i32_e32 v35, 3, v34
	v_and_b32_e32 v0, 0x70, v0
	s_addc_u32 s11, s3, s1
	v_lshl_or_b32 v0, v35, 11, v0
	v_lshl_add_u64 v[26:27], s[10:11], 0, v[0:1]
	v_add_co_u32_e32 v10, vcc, s52, v26
	v_lshl_add_u64 v[28:29], s[8:9], 0, v[0:1]
	s_nop 0
	v_addc_co_u32_e32 v11, vcc, 0, v27, vcc
	v_add_co_u32_e32 v14, vcc, s52, v28
	global_load_dwordx4 v[2:5], v0, s[10:11]
	global_load_dwordx4 v[6:9], v0, s[8:9]
	v_addc_co_u32_e32 v15, vcc, 0, v29, vcc
	v_add_co_u32_e32 v18, vcc, s56, v26
	global_load_dwordx4 v[10:13], v[10:11], off
	s_nop 0
	global_load_dwordx4 v[14:17], v[14:15], off
	v_addc_co_u32_e32 v19, vcc, 0, v27, vcc
	v_add_co_u32_e32 v22, vcc, s56, v28
	v_readlane_b32 s8, v250, 9
	s_nop 0
	v_addc_co_u32_e32 v23, vcc, 0, v29, vcc
	v_add_co_u32_e32 v26, vcc, s57, v26
	global_load_dwordx4 v[18:21], v[18:19], off
	s_nop 0
	global_load_dwordx4 v[22:25], v[22:23], off
	v_addc_co_u32_e32 v27, vcc, 0, v27, vcc
	v_add_co_u32_e32 v30, vcc, s57, v28
	v_lshrrev_b32_e32 v36, 1, v35
	s_nop 0
	v_addc_co_u32_e32 v31, vcc, 0, v29, vcc
	global_load_dwordx4 v[26:29], v[26:27], off
	s_nop 0
	global_load_dwordx4 v[30:33], v[30:31], off
	v_readlane_b32 s10, v250, 11
	v_xor_b32_e32 v34, v36, v34
	v_readlane_b32 s11, v250, 12
	s_add_u32 s6, s10, s6
	v_lshlrev_b32_e32 v35, 7, v35
	v_lshlrev_b32_e32 v34, 4, v34
	s_addc_u32 s7, s11, s7
	v_and_or_b32 v198, v34, s55, v35
	v_readlane_b32 s9, v250, 10
	s_add_u32 s8, s10, s0
	s_mov_b32 s3, 0
	v_add_u32_e32 v199, 0x10000, v198
	s_addc_u32 s9, s11, s1
	s_waitcnt vmcnt(7)
	ds_write_b128 v198, v[2:5]
	s_waitcnt vmcnt(6)
	ds_write_b128 v199, v[6:9]
	s_waitcnt vmcnt(5)
	ds_write_b128 v198, v[10:13] offset:8192
	s_waitcnt vmcnt(4)
	ds_write_b128 v199, v[14:17] offset:8192
	s_waitcnt vmcnt(3)
	ds_write_b128 v198, v[18:21] offset:16384
	s_waitcnt vmcnt(2)
	ds_write_b128 v199, v[22:25] offset:16384
	s_waitcnt vmcnt(1)
	ds_write_b128 v198, v[26:29] offset:24576
	s_waitcnt vmcnt(0)
	ds_write_b128 v199, v[30:33] offset:24576
	s_waitcnt lgkmcnt(0)
	s_barrier
	s_add_u32 s18, s6, 0xd800080
	s_addc_u32 s19, s7, 0
	s_add_u32 s22, s18, 0x20000
	s_addc_u32 s23, s19, 0
	s_add_u32 s24, s18, 0x40000
	s_addc_u32 s25, s19, 0
	s_add_u32 s26, s18, 0x60000
	s_addc_u32 s27, s19, 0
	s_add_u32 s6, s8, 0x5600080
	s_addc_u32 s7, s9, 0
	s_add_u32 s8, s6, 0x20000
	s_addc_u32 s9, s7, 0
	s_add_u32 s10, s6, 0x40000
	s_addc_u32 s11, s7, 0
	s_add_u32 s12, s6, 0x60000
	s_addc_u32 s13, s7, 0
	v_lshrrev_b32_e32 v170, 3, v204
	v_lshrrev_b32_e32 v171, 4, v204
	v_xor_b32_e32 v171, v171, v204
	v_and_b32_e32 v171, 7, v171
	v_lshlrev_b32_e32 v171, 4, v171
	v_lshl_or_b32 v170, v170, 11, v171
	v_readfirstlane_b32 s28, v204
	s_and_b32 s28, s28, 0x3c0
	s_lshl_b32 s28, s28, 4
	s_mov_b32 s3, 0
	ds_read_b128 v[130:133], v190
	ds_read_b128 v[138:141], v186
	ds_read_b128 v[134:137], v190 offset:4096
	ds_read_b128 v[142:145], v186 offset:4096
	ds_read_b128 v[146:149], v186 offset:8192
	ds_read_b128 v[150:153], v186 offset:12288
	s_add_u32 m0, s28, 0x8000
	s_nop 0
	global_load_lds_dwordx4 v170, s[6:7]
	s_add_u32 m0, s28, 0x18000
	s_nop 0
	global_load_lds_dwordx4 v170, s[18:19]
	s_add_u32 m0, s28, 0xa000
	s_nop 0
	global_load_lds_dwordx4 v170, s[8:9]
	s_add_u32 m0, s28, 0x1a000
	s_nop 0
	global_load_lds_dwordx4 v170, s[22:23]
	s_add_u32 m0, s28, 0xc000
	s_nop 0
	global_load_lds_dwordx4 v170, s[10:11]
	s_add_u32 m0, s28, 0x1c000
	s_nop 0
	global_load_lds_dwordx4 v170, s[24:25]
	s_add_u32 m0, s28, 0xe000
	s_nop 0
	global_load_lds_dwordx4 v170, s[12:13]
	s_add_u32 m0, s28, 0x1e000
	s_nop 0
	global_load_lds_dwordx4 v170, s[26:27]
	ds_read_b128 v[154:157], v191
	ds_read_b128 v[162:165], v187
	ds_read_b128 v[158:161], v191 offset:4096
	ds_read_b128 v[166:169], v187 offset:4096
	ds_read_b128 v[200:203], v187 offset:8192
	ds_read_b128 v[216:219], v187 offset:12288
	s_waitcnt lgkmcnt(6)
	v_mfma_f32_32x32x16_bf16 v[82:97], v[130:133], v[138:141], 0
	s_add_u32 s6, s6, 0x80
	s_addc_u32 s7, s7, 0
	v_mfma_f32_32x32x16_bf16 v[114:129], v[134:137], v[138:141], 0
	s_add_u32 s8, s8, 0x80
	s_addc_u32 s9, s9, 0
	v_mfma_f32_32x32x16_bf16 v[66:81], v[130:133], v[142:145], 0
	s_add_u32 s10, s10, 0x80
	s_addc_u32 s11, s11, 0
	v_mfma_f32_32x32x16_bf16 v[98:113], v[134:137], v[142:145], 0
	s_add_u32 s12, s12, 0x80
	s_addc_u32 s13, s13, 0
	v_mfma_f32_32x32x16_bf16 v[18:33], v[130:133], v[146:149], 0
	s_add_u32 s18, s18, 0x80
	s_addc_u32 s19, s19, 0
	v_mfma_f32_32x32x16_bf16 v[50:65], v[134:137], v[146:149], 0
	s_add_u32 s22, s22, 0x80
	s_addc_u32 s23, s23, 0
	v_mfma_f32_32x32x16_bf16 v[2:17], v[130:133], v[150:153], 0
	s_add_u32 s24, s24, 0x80
	s_addc_u32 s25, s25, 0
	v_mfma_f32_32x32x16_bf16 v[34:49], v[134:137], v[150:153], 0
	s_add_u32 s26, s26, 0x80
	s_addc_u32 s27, s27, 0
	s_branch .Lg_cout_mid2

.Lg_cout_mid2:
	ds_read_b128 v[130:133], v192
	ds_read_b128 v[138:141], v188
	ds_read_b128 v[134:137], v192 offset:4096
	ds_read_b128 v[142:145], v188 offset:4096
	ds_read_b128 v[146:149], v188 offset:8192
	ds_read_b128 v[150:153], v188 offset:12288
	s_waitcnt lgkmcnt(6)
	v_mfma_f32_32x32x16_bf16 v[82:97], v[154:157], v[162:165], v[82:97]
	v_mfma_f32_32x32x16_bf16 v[114:129], v[158:161], v[162:165], v[114:129]
	v_mfma_f32_32x32x16_bf16 v[66:81], v[154:157], v[166:169], v[66:81]
	v_mfma_f32_32x32x16_bf16 v[98:113], v[158:161], v[166:169], v[98:113]
	v_mfma_f32_32x32x16_bf16 v[18:33], v[154:157], v[200:203], v[18:33]
	v_mfma_f32_32x32x16_bf16 v[50:65], v[158:161], v[200:203], v[50:65]
	v_mfma_f32_32x32x16_bf16 v[2:17], v[154:157], v[216:219], v[2:17]
	v_mfma_f32_32x32x16_bf16 v[34:49], v[158:161], v[216:219], v[34:49]
	ds_read_b128 v[154:157], v193
	ds_read_b128 v[162:165], v189
	ds_read_b128 v[158:161], v193 offset:4096
	ds_read_b128 v[166:169], v189 offset:4096
	ds_read_b128 v[200:203], v189 offset:8192
	ds_read_b128 v[216:219], v189 offset:12288
	s_waitcnt lgkmcnt(6)
	v_mfma_f32_32x32x16_bf16 v[82:97], v[130:133], v[138:141], v[82:97]
	v_mfma_f32_32x32x16_bf16 v[114:129], v[134:137], v[138:141], v[114:129]
	v_mfma_f32_32x32x16_bf16 v[66:81], v[130:133], v[142:145], v[66:81]
	v_mfma_f32_32x32x16_bf16 v[98:113], v[134:137], v[142:145], v[98:113]
	v_mfma_f32_32x32x16_bf16 v[18:33], v[130:133], v[146:149], v[18:33]
	v_mfma_f32_32x32x16_bf16 v[50:65], v[134:137], v[146:149], v[50:65]
	v_mfma_f32_32x32x16_bf16 v[2:17], v[130:133], v[150:153], v[2:17]
	v_mfma_f32_32x32x16_bf16 v[34:49], v[134:137], v[150:153], v[34:49]
	s_waitcnt vmcnt(0) lgkmcnt(0)
	s_barrier
	ds_read_b128 v[130:133], v190 offset:32768
	ds_read_b128 v[138:141], v194
	ds_read_b128 v[134:137], v190 offset:36864
	ds_read_b128 v[142:145], v194 offset:4096
	ds_read_b128 v[146:149], v194 offset:8192
	ds_read_b128 v[150:153], v194 offset:12288
	s_cmp_ge_u32 s3, 14
	s_cbranch_scc1 .Lg_cout_nodma
	s_add_u32 m0, s28, 0x0
	v_mfma_f32_32x32x16_bf16 v[82:97], v[154:157], v[162:165], v[82:97]
	global_load_lds_dwordx4 v170, s[6:7]
	s_add_u32 m0, s28, 0x10000
	v_mfma_f32_32x32x16_bf16 v[114:129], v[158:161], v[162:165], v[114:129]
	global_load_lds_dwordx4 v170, s[18:19]
	s_add_u32 m0, s28, 0x2000
	v_mfma_f32_32x32x16_bf16 v[66:81], v[154:157], v[166:169], v[66:81]
	global_load_lds_dwordx4 v170, s[8:9]
	s_add_u32 m0, s28, 0x12000
	v_mfma_f32_32x32x16_bf16 v[98:113], v[158:161], v[166:169], v[98:113]
	global_load_lds_dwordx4 v170, s[22:23]
	s_add_u32 m0, s28, 0x4000
	v_mfma_f32_32x32x16_bf16 v[18:33], v[154:157], v[200:203], v[18:33]
	global_load_lds_dwordx4 v170, s[10:11]
	s_add_u32 m0, s28, 0x14000
	v_mfma_f32_32x32x16_bf16 v[50:65], v[158:161], v[200:203], v[50:65]
	global_load_lds_dwordx4 v170, s[24:25]
	s_add_u32 m0, s28, 0x6000
	v_mfma_f32_32x32x16_bf16 v[2:17], v[154:157], v[216:219], v[2:17]
	global_load_lds_dwordx4 v170, s[12:13]
	s_add_u32 m0, s28, 0x16000
	v_mfma_f32_32x32x16_bf16 v[34:49], v[158:161], v[216:219], v[34:49]
	global_load_lds_dwordx4 v170, s[26:27]
	s_branch .Lg_cout_join

.LBB0_1243:
	s_or_b64 exec, exec, s[10:11]
	v_readlane_b32 s12, v250, 9
	v_readlane_b32 s14, v250, 11
	v_readlane_b32 s15, v250, 12
	s_add_u32 s8, s14, s8
	s_addc_u32 s9, s15, s9
	s_add_u32 s10, s18, s0
	s_addc_u32 s11, s19, s1
	s_mov_b32 s3, 0
	v_readlane_b32 s13, v250, 10
	s_add_u32 s22, s8, 0x5800080
	s_addc_u32 s23, s9, 0
	s_add_u32 s24, s22, 0x20000
	s_addc_u32 s25, s23, 0
	s_add_u32 s26, s22, 0x40000
	s_addc_u32 s27, s23, 0
	s_add_u32 s28, s22, 0x60000
	s_addc_u32 s29, s23, 0
	s_add_u32 s8, s10, 0x4000080
	s_addc_u32 s9, s11, 0
	s_add_u32 s10, s8, 0x20000
	s_addc_u32 s11, s9, 0
	s_add_u32 s12, s8, 0x40000
	s_addc_u32 s13, s9, 0
	s_add_u32 s14, s8, 0x60000
	s_addc_u32 s15, s9, 0
	v_lshrrev_b32_e32 v170, 3, v204
	v_lshrrev_b32_e32 v171, 4, v204
	v_xor_b32_e32 v171, v171, v204
	v_and_b32_e32 v171, 7, v171
	v_lshlrev_b32_e32 v171, 4, v171
	v_lshl_or_b32 v170, v170, 11, v171
	v_readfirstlane_b32 s30, v204
	s_and_b32 s30, s30, 0x3c0
	s_lshl_b32 s30, s30, 4
	s_mov_b32 s3, 0
	ds_read_b128 v[130:133], v220
	ds_read_b128 v[138:141], v203
	ds_read_b128 v[134:137], v220 offset:4096
	ds_read_b128 v[142:145], v203 offset:4096
	ds_read_b128 v[146:149], v203 offset:8192
	ds_read_b128 v[150:153], v203 offset:12288
	s_add_u32 m0, s30, 0x8000
	s_nop 0
	global_load_lds_dwordx4 v170, s[8:9]
	s_add_u32 m0, s30, 0x18000
	s_nop 0
	global_load_lds_dwordx4 v170, s[22:23]
	s_add_u32 m0, s30, 0xa000
	s_nop 0
	global_load_lds_dwordx4 v170, s[10:11]
	s_add_u32 m0, s30, 0x1a000
	s_nop 0
	global_load_lds_dwordx4 v170, s[24:25]
	s_add_u32 m0, s30, 0xc000
	s_nop 0
	global_load_lds_dwordx4 v170, s[12:13]
	s_add_u32 m0, s30, 0x1c000
	s_nop 0
	global_load_lds_dwordx4 v170, s[26:27]
	s_add_u32 m0, s30, 0xe000
	s_nop 0
	global_load_lds_dwordx4 v170, s[14:15]
	s_add_u32 m0, s30, 0x1e000
	s_nop 0
	global_load_lds_dwordx4 v170, s[28:29]
	ds_read_b128 v[154:157], v221
	ds_read_b128 v[162:165], v216
	ds_read_b128 v[158:161], v221 offset:4096
	ds_read_b128 v[166:169], v216 offset:4096
	ds_read_b128 v[176:179], v216 offset:8192
	ds_read_b128 v[180:183], v216 offset:12288
	s_waitcnt lgkmcnt(6)
	v_mfma_f32_32x32x16_bf16 v[98:113], v[130:133], v[138:141], 0
	s_add_u32 s8, s8, 0x80
	s_addc_u32 s9, s9, 0
	v_mfma_f32_32x32x16_bf16 v[114:129], v[134:137], v[138:141], 0
	s_add_u32 s10, s10, 0x80
	s_addc_u32 s11, s11, 0
	v_mfma_f32_32x32x16_bf16 v[82:97], v[130:133], v[142:145], 0
	s_add_u32 s12, s12, 0x80
	s_addc_u32 s13, s13, 0
	v_mfma_f32_32x32x16_bf16 v[66:81], v[134:137], v[142:145], 0
	s_add_u32 s14, s14, 0x80
	s_addc_u32 s15, s15, 0
	v_mfma_f32_32x32x16_bf16 v[34:49], v[130:133], v[146:149], 0
	s_add_u32 s22, s22, 0x80
	s_addc_u32 s23, s23, 0
	v_mfma_f32_32x32x16_bf16 v[50:65], v[134:137], v[146:149], 0
	s_add_u32 s24, s24, 0x80
	s_addc_u32 s25, s25, 0
	v_mfma_f32_32x32x16_bf16 v[18:33], v[130:133], v[150:153], 0
	s_add_u32 s26, s26, 0x80
	s_addc_u32 s27, s27, 0
	v_mfma_f32_32x32x16_bf16 v[2:17], v[134:137], v[150:153], 0
	s_add_u32 s28, s28, 0x80
	s_addc_u32 s29, s29, 0
	s_branch .Lg_aqkv_mid2

.Lg_aqkv_mid2:
	ds_read_b128 v[130:133], v222
	ds_read_b128 v[138:141], v217
	ds_read_b128 v[134:137], v222 offset:4096
	ds_read_b128 v[142:145], v217 offset:4096
	ds_read_b128 v[146:149], v217 offset:8192
	ds_read_b128 v[150:153], v217 offset:12288
	s_waitcnt lgkmcnt(6)
	v_mfma_f32_32x32x16_bf16 v[98:113], v[154:157], v[162:165], v[98:113]
	v_mfma_f32_32x32x16_bf16 v[114:129], v[158:161], v[162:165], v[114:129]
	v_mfma_f32_32x32x16_bf16 v[82:97], v[154:157], v[166:169], v[82:97]
	v_mfma_f32_32x32x16_bf16 v[66:81], v[158:161], v[166:169], v[66:81]
	v_mfma_f32_32x32x16_bf16 v[34:49], v[154:157], v[176:179], v[34:49]
	v_mfma_f32_32x32x16_bf16 v[50:65], v[158:161], v[176:179], v[50:65]
	v_mfma_f32_32x32x16_bf16 v[18:33], v[154:157], v[180:183], v[18:33]
	v_mfma_f32_32x32x16_bf16 v[2:17], v[158:161], v[180:183], v[2:17]
	ds_read_b128 v[154:157], v223
	ds_read_b128 v[162:165], v218
	ds_read_b128 v[158:161], v223 offset:4096
	ds_read_b128 v[166:169], v218 offset:4096
	ds_read_b128 v[176:179], v218 offset:8192
	ds_read_b128 v[180:183], v218 offset:12288
	s_waitcnt lgkmcnt(6)
	v_mfma_f32_32x32x16_bf16 v[98:113], v[130:133], v[138:141], v[98:113]
	v_mfma_f32_32x32x16_bf16 v[114:129], v[134:137], v[138:141], v[114:129]
	v_mfma_f32_32x32x16_bf16 v[82:97], v[130:133], v[142:145], v[82:97]
	v_mfma_f32_32x32x16_bf16 v[66:81], v[134:137], v[142:145], v[66:81]
	v_mfma_f32_32x32x16_bf16 v[34:49], v[130:133], v[146:149], v[34:49]
	v_mfma_f32_32x32x16_bf16 v[50:65], v[134:137], v[146:149], v[50:65]
	v_mfma_f32_32x32x16_bf16 v[18:33], v[130:133], v[150:153], v[18:33]
	v_mfma_f32_32x32x16_bf16 v[2:17], v[134:137], v[150:153], v[2:17]
	s_waitcnt vmcnt(0) lgkmcnt(0)
	s_barrier
	ds_read_b128 v[130:133], v220 offset:32768
	ds_read_b128 v[138:141], v224
	ds_read_b128 v[134:137], v220 offset:36864
	ds_read_b128 v[142:145], v224 offset:4096
	ds_read_b128 v[146:149], v224 offset:8192
	ds_read_b128 v[150:153], v224 offset:12288
	s_cmp_ge_u32 s3, 14
	s_cbranch_scc1 .Lg_aqkv_nodma
	s_add_u32 m0, s30, 0x0
	v_mfma_f32_32x32x16_bf16 v[98:113], v[154:157], v[162:165], v[98:113]
	global_load_lds_dwordx4 v170, s[8:9]
	s_add_u32 m0, s30, 0x10000
	v_mfma_f32_32x32x16_bf16 v[114:129], v[158:161], v[162:165], v[114:129]
	global_load_lds_dwordx4 v170, s[22:23]
	s_add_u32 m0, s30, 0x2000
	v_mfma_f32_32x32x16_bf16 v[82:97], v[154:157], v[166:169], v[82:97]
	global_load_lds_dwordx4 v170, s[10:11]
	s_add_u32 m0, s30, 0x12000
	v_mfma_f32_32x32x16_bf16 v[66:81], v[158:161], v[166:169], v[66:81]
	global_load_lds_dwordx4 v170, s[24:25]
	s_add_u32 m0, s30, 0x4000
	v_mfma_f32_32x32x16_bf16 v[34:49], v[154:157], v[176:179], v[34:49]
	global_load_lds_dwordx4 v170, s[12:13]
	s_add_u32 m0, s30, 0x14000
	v_mfma_f32_32x32x16_bf16 v[50:65], v[158:161], v[176:179], v[50:65]
	global_load_lds_dwordx4 v170, s[26:27]
	s_add_u32 m0, s30, 0x6000
	v_mfma_f32_32x32x16_bf16 v[18:33], v[154:157], v[180:183], v[18:33]
	global_load_lds_dwordx4 v170, s[14:15]
	s_add_u32 m0, s30, 0x16000
	v_mfma_f32_32x32x16_bf16 v[2:17], v[158:161], v[180:183], v[2:17]
	global_load_lds_dwordx4 v170, s[28:29]
	s_branch .Lg_aqkv_join

.LBB0_1508:
	s_bfe_u32 s4, s18, 0x20003
	s_lshr_b32 s0, s18, 5
	s_lshl_b32 s0, s0, 3
	s_and_b32 s1, s18, 7
	s_add_i32 s0, s0, s1
	s_lshl_b32 s2, s0, 8
	s_ashr_i32 s3, s2, 31
	s_ashr_i32 s5, s4, 31
	s_lshl_b64 s[0:1], s[4:5], 19
	s_lshl_b64 s[6:7], s[2:3], 11
	v_readlane_b32 s8, v252, 31
	v_readlane_b32 s9, v252, 32
	s_add_u32 s8, s8, s6
	v_mov_b32_e32 v34, v174
	s_addc_u32 s9, s9, s7
	s_add_u32 s10, s14, s0
	v_lshlrev_b32_e32 v0, 4, v34
	v_ashrrev_i32_e32 v35, 3, v34
	v_and_b32_e32 v0, 0x70, v0
	s_addc_u32 s11, s15, s1
	v_lshl_or_b32 v0, v35, 11, v0
	v_lshl_add_u64 v[26:27], s[10:11], 0, v[0:1]
	v_add_co_u32_e32 v10, vcc, s52, v26
	v_lshl_add_u64 v[28:29], s[8:9], 0, v[0:1]
	s_nop 0
	v_addc_co_u32_e32 v11, vcc, 0, v27, vcc
	v_add_co_u32_e32 v14, vcc, s52, v28
	global_load_dwordx4 v[2:5], v0, s[10:11]
	global_load_dwordx4 v[6:9], v0, s[8:9]
	v_addc_co_u32_e32 v15, vcc, 0, v29, vcc
	v_add_co_u32_e32 v18, vcc, s56, v26
	global_load_dwordx4 v[10:13], v[10:11], off
	s_nop 0
	global_load_dwordx4 v[14:17], v[14:15], off
	v_addc_co_u32_e32 v19, vcc, 0, v27, vcc
	v_add_co_u32_e32 v22, vcc, s56, v28
	v_readlane_b32 s8, v250, 9
	s_nop 0
	v_addc_co_u32_e32 v23, vcc, 0, v29, vcc
	v_add_co_u32_e32 v26, vcc, s57, v26
	global_load_dwordx4 v[18:21], v[18:19], off
	s_nop 0
	global_load_dwordx4 v[22:25], v[22:23], off
	v_addc_co_u32_e32 v27, vcc, 0, v27, vcc
	v_add_co_u32_e32 v30, vcc, s57, v28
	v_lshrrev_b32_e32 v36, 1, v35
	s_nop 0
	v_addc_co_u32_e32 v31, vcc, 0, v29, vcc
	global_load_dwordx4 v[26:29], v[26:27], off
	s_nop 0
	global_load_dwordx4 v[30:33], v[30:31], off
	v_readlane_b32 s10, v250, 11
	v_xor_b32_e32 v34, v36, v34
	v_readlane_b32 s11, v250, 12
	s_add_u32 s6, s10, s6
	v_lshlrev_b32_e32 v35, 7, v35
	v_lshlrev_b32_e32 v34, 4, v34
	s_addc_u32 s7, s11, s7
	v_and_or_b32 v198, v34, s55, v35
	v_readlane_b32 s9, v250, 10
	s_add_u32 s8, s16, s0
	s_mov_b32 s3, 0
	v_add_u32_e32 v199, 0x10000, v198
	s_addc_u32 s9, s17, s1
	s_waitcnt vmcnt(7)
	ds_write_b128 v198, v[2:5]
	s_waitcnt vmcnt(6)
	ds_write_b128 v199, v[6:9]
	s_waitcnt vmcnt(5)
	ds_write_b128 v198, v[10:13] offset:8192
	s_waitcnt vmcnt(4)
	ds_write_b128 v199, v[14:17] offset:8192
	s_waitcnt vmcnt(3)
	ds_write_b128 v198, v[18:21] offset:16384
	s_waitcnt vmcnt(2)
	ds_write_b128 v199, v[22:25] offset:16384
	s_waitcnt vmcnt(1)
	ds_write_b128 v198, v[26:29] offset:24576
	s_waitcnt vmcnt(0)
	ds_write_b128 v199, v[30:33] offset:24576
	s_waitcnt lgkmcnt(0)
	s_barrier
	s_add_u32 s22, s6, 0xd800080
	s_addc_u32 s23, s7, 0
	s_add_u32 s24, s22, 0x20000
	s_addc_u32 s25, s23, 0
	s_add_u32 s26, s22, 0x40000
	s_addc_u32 s27, s23, 0
	s_add_u32 s28, s22, 0x60000
	s_addc_u32 s29, s23, 0
	s_add_u32 s6, s8, 0x4c00080
	s_addc_u32 s7, s9, 0
	s_add_u32 s8, s6, 0x20000
	s_addc_u32 s9, s7, 0
	s_add_u32 s10, s6, 0x40000
	s_addc_u32 s11, s7, 0
	s_add_u32 s12, s6, 0x60000
	s_addc_u32 s13, s7, 0
	v_lshrrev_b32_e32 v170, 3, v204
	v_lshrrev_b32_e32 v171, 4, v204
	v_xor_b32_e32 v171, v171, v204
	v_and_b32_e32 v171, 7, v171
	v_lshlrev_b32_e32 v171, 4, v171
	v_lshl_or_b32 v170, v170, 11, v171
	v_readfirstlane_b32 s30, v204
	s_and_b32 s30, s30, 0x3c0
	s_lshl_b32 s30, s30, 4
	s_mov_b32 s3, 0
	ds_read_b128 v[130:133], v186
	ds_read_b128 v[138:141], v182
	ds_read_b128 v[134:137], v186 offset:4096
	ds_read_b128 v[142:145], v182 offset:4096
	ds_read_b128 v[146:149], v182 offset:8192
	ds_read_b128 v[150:153], v182 offset:12288
	s_add_u32 m0, s30, 0x8000
	s_nop 0
	global_load_lds_dwordx4 v170, s[6:7]
	s_add_u32 m0, s30, 0x18000
	s_nop 0
	global_load_lds_dwordx4 v170, s[22:23]
	s_add_u32 m0, s30, 0xa000
	s_nop 0
	global_load_lds_dwordx4 v170, s[8:9]
	s_add_u32 m0, s30, 0x1a000
	s_nop 0
	global_load_lds_dwordx4 v170, s[24:25]
	s_add_u32 m0, s30, 0xc000
	s_nop 0
	global_load_lds_dwordx4 v170, s[10:11]
	s_add_u32 m0, s30, 0x1c000
	s_nop 0
	global_load_lds_dwordx4 v170, s[26:27]
	s_add_u32 m0, s30, 0xe000
	s_nop 0
	global_load_lds_dwordx4 v170, s[12:13]
	s_add_u32 m0, s30, 0x1e000
	s_nop 0
	global_load_lds_dwordx4 v170, s[28:29]
	ds_read_b128 v[154:157], v187
	ds_read_b128 v[162:165], v183
	ds_read_b128 v[158:161], v187 offset:4096
	ds_read_b128 v[166:169], v183 offset:4096
	ds_read_b128 v[200:203], v183 offset:8192
	ds_read_b128 v[216:219], v183 offset:12288
	s_waitcnt lgkmcnt(6)
	v_mfma_f32_32x32x16_bf16 v[82:97], v[130:133], v[138:141], 0
	s_add_u32 s6, s6, 0x80
	s_addc_u32 s7, s7, 0
	v_mfma_f32_32x32x16_bf16 v[114:129], v[134:137], v[138:141], 0
	s_add_u32 s8, s8, 0x80
	s_addc_u32 s9, s9, 0
	v_mfma_f32_32x32x16_bf16 v[66:81], v[130:133], v[142:145], 0
	s_add_u32 s10, s10, 0x80
	s_addc_u32 s11, s11, 0
	v_mfma_f32_32x32x16_bf16 v[98:113], v[134:137], v[142:145], 0
	s_add_u32 s12, s12, 0x80
	s_addc_u32 s13, s13, 0
	v_mfma_f32_32x32x16_bf16 v[18:33], v[130:133], v[146:149], 0
	s_add_u32 s22, s22, 0x80
	s_addc_u32 s23, s23, 0
	v_mfma_f32_32x32x16_bf16 v[50:65], v[134:137], v[146:149], 0
	s_add_u32 s24, s24, 0x80
	s_addc_u32 s25, s25, 0
	v_mfma_f32_32x32x16_bf16 v[2:17], v[130:133], v[150:153], 0
	s_add_u32 s26, s26, 0x80
	s_addc_u32 s27, s27, 0
	v_mfma_f32_32x32x16_bf16 v[34:49], v[134:137], v[150:153], 0
	s_add_u32 s28, s28, 0x80
	s_addc_u32 s29, s29, 0
	s_branch .Lg_aout_mid2

.Lg_aout_mid2:
	ds_read_b128 v[130:133], v192
	ds_read_b128 v[138:141], v184
	ds_read_b128 v[134:137], v192 offset:4096
	ds_read_b128 v[142:145], v184 offset:4096
	ds_read_b128 v[146:149], v184 offset:8192
	ds_read_b128 v[150:153], v184 offset:12288
	s_waitcnt lgkmcnt(6)
	v_mfma_f32_32x32x16_bf16 v[82:97], v[154:157], v[162:165], v[82:97]
	v_mfma_f32_32x32x16_bf16 v[114:129], v[158:161], v[162:165], v[114:129]
	v_mfma_f32_32x32x16_bf16 v[66:81], v[154:157], v[166:169], v[66:81]
	v_mfma_f32_32x32x16_bf16 v[98:113], v[158:161], v[166:169], v[98:113]
	v_mfma_f32_32x32x16_bf16 v[18:33], v[154:157], v[200:203], v[18:33]
	v_mfma_f32_32x32x16_bf16 v[50:65], v[158:161], v[200:203], v[50:65]
	v_mfma_f32_32x32x16_bf16 v[2:17], v[154:157], v[216:219], v[2:17]
	v_mfma_f32_32x32x16_bf16 v[34:49], v[158:161], v[216:219], v[34:49]
	ds_read_b128 v[154:157], v193
	ds_read_b128 v[162:165], v185
	ds_read_b128 v[158:161], v193 offset:4096
	ds_read_b128 v[166:169], v185 offset:4096
	ds_read_b128 v[200:203], v185 offset:8192
	ds_read_b128 v[216:219], v185 offset:12288
	s_waitcnt lgkmcnt(6)
	v_mfma_f32_32x32x16_bf16 v[82:97], v[130:133], v[138:141], v[82:97]
	v_mfma_f32_32x32x16_bf16 v[114:129], v[134:137], v[138:141], v[114:129]
	v_mfma_f32_32x32x16_bf16 v[66:81], v[130:133], v[142:145], v[66:81]
	v_mfma_f32_32x32x16_bf16 v[98:113], v[134:137], v[142:145], v[98:113]
	v_mfma_f32_32x32x16_bf16 v[18:33], v[130:133], v[146:149], v[18:33]
	v_mfma_f32_32x32x16_bf16 v[50:65], v[134:137], v[146:149], v[50:65]
	v_mfma_f32_32x32x16_bf16 v[2:17], v[130:133], v[150:153], v[2:17]
	v_mfma_f32_32x32x16_bf16 v[34:49], v[134:137], v[150:153], v[34:49]
	s_waitcnt vmcnt(0) lgkmcnt(0)
	s_barrier
	ds_read_b128 v[130:133], v186 offset:32768
	ds_read_b128 v[138:141], v194
	ds_read_b128 v[134:137], v186 offset:36864
	ds_read_b128 v[142:145], v194 offset:4096
	ds_read_b128 v[146:149], v194 offset:8192
	ds_read_b128 v[150:153], v194 offset:12288
	s_cmp_ge_u32 s3, 14
	s_cbranch_scc1 .Lg_aout_nodma
	s_add_u32 m0, s30, 0x0
	v_mfma_f32_32x32x16_bf16 v[82:97], v[154:157], v[162:165], v[82:97]
	global_load_lds_dwordx4 v170, s[6:7]
	s_add_u32 m0, s30, 0x10000
	v_mfma_f32_32x32x16_bf16 v[114:129], v[158:161], v[162:165], v[114:129]
	global_load_lds_dwordx4 v170, s[22:23]
	s_add_u32 m0, s30, 0x2000
	v_mfma_f32_32x32x16_bf16 v[66:81], v[154:157], v[166:169], v[66:81]
	global_load_lds_dwordx4 v170, s[8:9]
	s_add_u32 m0, s30, 0x12000
	v_mfma_f32_32x32x16_bf16 v[98:113], v[158:161], v[166:169], v[98:113]
	global_load_lds_dwordx4 v170, s[24:25]
	s_add_u32 m0, s30, 0x4000
	v_mfma_f32_32x32x16_bf16 v[18:33], v[154:157], v[200:203], v[18:33]
	global_load_lds_dwordx4 v170, s[10:11]
	s_add_u32 m0, s30, 0x14000
	v_mfma_f32_32x32x16_bf16 v[50:65], v[158:161], v[200:203], v[50:65]
	global_load_lds_dwordx4 v170, s[26:27]
	s_add_u32 m0, s30, 0x6000
	v_mfma_f32_32x32x16_bf16 v[2:17], v[154:157], v[216:219], v[2:17]
	global_load_lds_dwordx4 v170, s[12:13]
	s_add_u32 m0, s30, 0x16000
	v_mfma_f32_32x32x16_bf16 v[34:49], v[158:161], v[216:219], v[34:49]
	global_load_lds_dwordx4 v170, s[28:29]
	s_branch .Lg_aout_join

.LBB0_1604:
	s_or_b64 exec, exec, s[10:11]
	v_readlane_b32 s12, v250, 9
	v_readlane_b32 s14, v250, 11
	v_readlane_b32 s15, v250, 12
	s_add_u32 s8, s14, s8
	s_addc_u32 s9, s15, s9
	v_readlane_b32 s5, v252, 57
	s_add_u32 s10, s5, s0
	v_readlane_b32 s5, v252, 58
	s_addc_u32 s11, s5, s1
	v_readlane_b32 s5, v252, 59
	v_readlane_b32 s13, v250, 10
	s_add_u32 s12, s5, s0
	v_readlane_b32 s5, v252, 60
	s_addc_u32 s13, s5, s1
	v_readlane_b32 s5, v252, 61
	s_add_u32 s14, s5, s0
	v_readlane_b32 s5, v252, 62
	s_addc_u32 s15, s5, s1
	v_readlane_b32 s5, v252, 63
	s_add_u32 s16, s5, s0
	v_readlane_b32 s5, v251, 0
	s_addc_u32 s17, s5, s1
	v_readlane_b32 s5, v251, 1
	s_add_u32 s18, s5, s0
	v_readlane_b32 s5, v251, 2
	s_addc_u32 s19, s5, s1
	v_readlane_b32 s5, v251, 3
	s_add_u32 s20, s5, s0
	v_readlane_b32 s5, v251, 4
	s_addc_u32 s21, s5, s1
	v_readlane_b32 s5, v251, 5
	s_add_u32 s22, s5, s0
	v_readlane_b32 s5, v251, 6
	s_addc_u32 s23, s5, s1
	v_readlane_b32 s5, v251, 7
	s_add_u32 s24, s5, s0
	v_readlane_b32 s0, v251, 8
	s_addc_u32 s25, s0, s1
	s_mov_b32 s5, 0
	s_mov_b64 s[26:27], s[8:9]
	s_mov_b32 s8, s10
	s_mov_b32 s9, s11
	s_add_u32 s10, s8, 0x20000
	s_addc_u32 s11, s9, 0
	s_add_u32 s12, s8, 0x40000
	s_addc_u32 s13, s9, 0
	s_add_u32 s14, s8, 0x60000
	s_addc_u32 s15, s9, 0
	s_add_u32 s16, s26, 0x5800080
	s_addc_u32 s17, s27, 0
	s_add_u32 s18, s16, 0x20000
	s_addc_u32 s19, s17, 0
	s_add_u32 s20, s16, 0x40000
	s_addc_u32 s21, s17, 0
	s_add_u32 s22, s16, 0x60000
	s_addc_u32 s23, s17, 0
	v_lshrrev_b32_e32 v170, 3, v204
	v_lshrrev_b32_e32 v171, 4, v204
	v_xor_b32_e32 v171, v171, v204
	v_and_b32_e32 v171, 7, v171
	v_lshlrev_b32_e32 v171, 4, v171
	v_lshl_or_b32 v170, v170, 11, v171
	v_readfirstlane_b32 s24, v204
	s_and_b32 s24, s24, 0x3c0
	s_lshl_b32 s24, s24, 4
	s_mov_b32 s5, 0
	ds_read_b128 v[130:133], v186
	ds_read_b128 v[138:141], v181
	ds_read_b128 v[134:137], v186 offset:4096
	ds_read_b128 v[142:145], v181 offset:4096
	ds_read_b128 v[146:149], v181 offset:8192
	ds_read_b128 v[150:153], v181 offset:12288
	s_add_u32 m0, s24, 0x8000
	s_nop 0
	global_load_lds_dwordx4 v170, s[8:9]
	s_add_u32 m0, s24, 0x18000
	s_nop 0
	global_load_lds_dwordx4 v170, s[16:17]
	s_add_u32 m0, s24, 0xa000
	s_nop 0
	global_load_lds_dwordx4 v170, s[10:11]
	s_add_u32 m0, s24, 0x1a000
	s_nop 0
	global_load_lds_dwordx4 v170, s[18:19]
	s_add_u32 m0, s24, 0xc000
	s_nop 0
	global_load_lds_dwordx4 v170, s[12:13]
	s_add_u32 m0, s24, 0x1c000
	s_nop 0
	global_load_lds_dwordx4 v170, s[20:21]
	s_add_u32 m0, s24, 0xe000
	s_nop 0
	global_load_lds_dwordx4 v170, s[14:15]
	s_add_u32 m0, s24, 0x1e000
	s_nop 0
	global_load_lds_dwordx4 v170, s[22:23]
	ds_read_b128 v[154:157], v187
	ds_read_b128 v[162:165], v182
	ds_read_b128 v[158:161], v187 offset:4096
	ds_read_b128 v[166:169], v182 offset:4096
	ds_read_b128 v[196:199], v182 offset:8192
	ds_read_b128 v[200:203], v182 offset:12288
	s_waitcnt lgkmcnt(6)
	v_mfma_f32_32x32x16_bf16 v[98:113], v[130:133], v[138:141], 0
	s_add_u32 s8, s8, 0x80
	s_addc_u32 s9, s9, 0
	v_mfma_f32_32x32x16_bf16 v[114:129], v[134:137], v[138:141], 0
	s_add_u32 s10, s10, 0x80
	s_addc_u32 s11, s11, 0
	v_mfma_f32_32x32x16_bf16 v[82:97], v[130:133], v[142:145], 0
	s_add_u32 s12, s12, 0x80
	s_addc_u32 s13, s13, 0
	v_mfma_f32_32x32x16_bf16 v[66:81], v[134:137], v[142:145], 0
	s_add_u32 s14, s14, 0x80
	s_addc_u32 s15, s15, 0
	v_mfma_f32_32x32x16_bf16 v[50:65], v[130:133], v[146:149], 0
	s_add_u32 s16, s16, 0x80
	s_addc_u32 s17, s17, 0
	v_mfma_f32_32x32x16_bf16 v[34:49], v[134:137], v[146:149], 0
	s_add_u32 s18, s18, 0x80
	s_addc_u32 s19, s19, 0
	v_mfma_f32_32x32x16_bf16 v[18:33], v[130:133], v[150:153], 0
	s_add_u32 s20, s20, 0x80
	s_addc_u32 s21, s21, 0
	v_mfma_f32_32x32x16_bf16 v[2:17], v[134:137], v[150:153], 0
	s_add_u32 s22, s22, 0x80
	s_addc_u32 s23, s23, 0
	s_branch .Lg_mlp1_mid2

.Lg_mlp1_mid2:
	ds_read_b128 v[130:133], v188
	ds_read_b128 v[138:141], v183
	ds_read_b128 v[134:137], v188 offset:4096
	ds_read_b128 v[142:145], v183 offset:4096
	ds_read_b128 v[146:149], v183 offset:8192
	ds_read_b128 v[150:153], v183 offset:12288
	s_waitcnt lgkmcnt(6)
	v_mfma_f32_32x32x16_bf16 v[98:113], v[154:157], v[162:165], v[98:113]
	v_mfma_f32_32x32x16_bf16 v[114:129], v[158:161], v[162:165], v[114:129]
	v_mfma_f32_32x32x16_bf16 v[82:97], v[154:157], v[166:169], v[82:97]
	v_mfma_f32_32x32x16_bf16 v[66:81], v[158:161], v[166:169], v[66:81]
	v_mfma_f32_32x32x16_bf16 v[50:65], v[154:157], v[196:199], v[50:65]
	v_mfma_f32_32x32x16_bf16 v[34:49], v[158:161], v[196:199], v[34:49]
	v_mfma_f32_32x32x16_bf16 v[18:33], v[154:157], v[200:203], v[18:33]
	v_mfma_f32_32x32x16_bf16 v[2:17], v[158:161], v[200:203], v[2:17]
	ds_read_b128 v[154:157], v189
	ds_read_b128 v[162:165], v184
	ds_read_b128 v[158:161], v189 offset:4096
	ds_read_b128 v[166:169], v184 offset:4096
	ds_read_b128 v[196:199], v184 offset:8192
	ds_read_b128 v[200:203], v184 offset:12288
	s_waitcnt lgkmcnt(6)
	v_mfma_f32_32x32x16_bf16 v[98:113], v[130:133], v[138:141], v[98:113]
	v_mfma_f32_32x32x16_bf16 v[114:129], v[134:137], v[138:141], v[114:129]
	v_mfma_f32_32x32x16_bf16 v[82:97], v[130:133], v[142:145], v[82:97]
	v_mfma_f32_32x32x16_bf16 v[66:81], v[134:137], v[142:145], v[66:81]
	v_mfma_f32_32x32x16_bf16 v[50:65], v[130:133], v[146:149], v[50:65]
	v_mfma_f32_32x32x16_bf16 v[34:49], v[134:137], v[146:149], v[34:49]
	v_mfma_f32_32x32x16_bf16 v[18:33], v[130:133], v[150:153], v[18:33]
	v_mfma_f32_32x32x16_bf16 v[2:17], v[134:137], v[150:153], v[2:17]
	s_waitcnt vmcnt(0) lgkmcnt(0)
	s_barrier
	ds_read_b128 v[130:133], v186 offset:32768
	ds_read_b128 v[138:141], v190
	ds_read_b128 v[134:137], v186 offset:36864
	ds_read_b128 v[142:145], v190 offset:4096
	ds_read_b128 v[146:149], v190 offset:8192
	ds_read_b128 v[150:153], v190 offset:12288
	s_cmp_ge_u32 s5, 14
	s_cbranch_scc1 .Lg_mlp1_nodma
	s_add_u32 m0, s24, 0x0
	v_mfma_f32_32x32x16_bf16 v[98:113], v[154:157], v[162:165], v[98:113]
	global_load_lds_dwordx4 v170, s[8:9]
	s_add_u32 m0, s24, 0x10000
	v_mfma_f32_32x32x16_bf16 v[114:129], v[158:161], v[162:165], v[114:129]
	global_load_lds_dwordx4 v170, s[16:17]
	s_add_u32 m0, s24, 0x2000
	v_mfma_f32_32x32x16_bf16 v[82:97], v[154:157], v[166:169], v[82:97]
	global_load_lds_dwordx4 v170, s[10:11]
	s_add_u32 m0, s24, 0x12000
	v_mfma_f32_32x32x16_bf16 v[66:81], v[158:161], v[166:169], v[66:81]
	global_load_lds_dwordx4 v170, s[18:19]
	s_add_u32 m0, s24, 0x4000
	v_mfma_f32_32x32x16_bf16 v[50:65], v[154:157], v[196:199], v[50:65]
	global_load_lds_dwordx4 v170, s[12:13]
	s_add_u32 m0, s24, 0x14000
	v_mfma_f32_32x32x16_bf16 v[34:49], v[158:161], v[196:199], v[34:49]
	global_load_lds_dwordx4 v170, s[20:21]
	s_add_u32 m0, s24, 0x6000
	v_mfma_f32_32x32x16_bf16 v[18:33], v[154:157], v[200:203], v[18:33]
	global_load_lds_dwordx4 v170, s[14:15]
	s_add_u32 m0, s24, 0x16000
	v_mfma_f32_32x32x16_bf16 v[2:17], v[158:161], v[200:203], v[2:17]
	global_load_lds_dwordx4 v170, s[22:23]
	s_branch .Lg_mlp1_join

.LBB0_1678:
	s_bfe_u32 s4, s30, 0x20003
	s_lshr_b32 s0, s30, 5
	s_lshl_b32 s0, s0, 3
	s_and_b32 s1, s30, 7
	s_add_i32 s0, s0, s1
	s_lshl_b32 s2, s0, 8
	s_ashr_i32 s3, s2, 31
	s_ashr_i32 s5, s4, 31
	s_lshl_b64 s[0:1], s[4:5], 21
	s_lshl_b64 s[6:7], s[2:3], 13
	v_readlane_b32 s8, v250, 48
	v_readlane_b32 s9, v250, 49
	s_add_u32 s8, s8, s6
	v_mov_b32_e32 v34, v172
	s_addc_u32 s9, s9, s7
	s_add_u32 s10, s28, s0
	v_lshlrev_b32_e32 v0, 4, v34
	v_ashrrev_i32_e32 v35, 3, v34
	v_and_b32_e32 v0, 0x70, v0
	s_addc_u32 s11, s29, s1
	v_lshl_or_b32 v0, v35, 13, v0
	v_lshl_add_u64 v[26:27], s[10:11], 0, v[0:1]
	s_mov_b32 s3, 0x80000
	v_add_co_u32_e32 v10, vcc, s3, v26
	v_lshl_add_u64 v[28:29], s[8:9], 0, v[0:1]
	s_nop 0
	v_addc_co_u32_e32 v11, vcc, 0, v27, vcc
	v_add_co_u32_e32 v14, vcc, s3, v28
	s_mov_b32 s3, 0x100000
	s_nop 0
	v_addc_co_u32_e32 v15, vcc, 0, v29, vcc
	v_add_co_u32_e32 v18, vcc, s3, v26
	global_load_dwordx4 v[2:5], v0, s[10:11]
	global_load_dwordx4 v[6:9], v0, s[8:9]
	v_addc_co_u32_e32 v19, vcc, 0, v27, vcc
	v_add_co_u32_e32 v22, vcc, s3, v28
	s_mov_b32 s3, 0x180000
	s_nop 0
	v_addc_co_u32_e32 v23, vcc, 0, v29, vcc
	v_add_co_u32_e32 v26, vcc, s3, v26
	global_load_dwordx4 v[10:13], v[10:11], off
	s_nop 0
	global_load_dwordx4 v[14:17], v[14:15], off
	v_addc_co_u32_e32 v27, vcc, 0, v27, vcc
	v_add_co_u32_e32 v30, vcc, s3, v28
	global_load_dwordx4 v[18:21], v[18:19], off
	s_nop 0
	global_load_dwordx4 v[22:25], v[22:23], off
	v_addc_co_u32_e32 v31, vcc, 0, v29, vcc
	global_load_dwordx4 v[26:29], v[26:27], off
	s_nop 0
	global_load_dwordx4 v[30:33], v[30:31], off
	v_readlane_b32 s8, v250, 9
	v_readlane_b32 s10, v250, 11
	v_readlane_b32 s11, v250, 12
	s_add_u32 s6, s10, s6
	s_addc_u32 s7, s11, s7
	v_readlane_b32 s5, v251, 9
	v_readlane_b32 s9, v250, 10
	s_add_u32 s8, s5, s0
	v_readlane_b32 s5, v251, 10
	s_addc_u32 s9, s5, s1
	v_readlane_b32 s5, v251, 11
	s_add_u32 s10, s5, s0
	v_readlane_b32 s5, v251, 12
	s_addc_u32 s11, s5, s1
	v_readlane_b32 s5, v251, 13
	s_add_u32 s12, s5, s0
	v_readlane_b32 s5, v251, 14
	s_addc_u32 s13, s5, s1
	v_readlane_b32 s5, v251, 15
	s_add_u32 s14, s5, s0
	v_readlane_b32 s5, v251, 16
	s_addc_u32 s15, s5, s1
	v_readlane_b32 s5, v251, 17
	s_add_u32 s16, s5, s0
	v_readlane_b32 s5, v251, 18
	s_addc_u32 s17, s5, s1
	v_readlane_b32 s5, v251, 19
	s_add_u32 s18, s5, s0
	v_readlane_b32 s5, v251, 20
	v_lshrrev_b32_e32 v36, 1, v35
	s_addc_u32 s19, s5, s1
	v_readlane_b32 s5, v251, 21
	v_xor_b32_e32 v34, v36, v34
	s_add_u32 s20, s5, s0
	v_readlane_b32 s5, v251, 22
	v_lshlrev_b32_e32 v35, 7, v35
	v_lshlrev_b32_e32 v34, 4, v34
	s_addc_u32 s21, s5, s1
	v_readlane_b32 s5, v251, 23
	v_and_or_b32 v192, v34, s55, v35
	s_add_u32 s22, s5, s0
	v_readlane_b32 s0, v251, 24
	s_mov_b32 s3, 0
	v_add_u32_e32 v193, 0x10000, v192
	s_addc_u32 s23, s0, s1
	s_waitcnt vmcnt(7)
	ds_write_b128 v192, v[2:5]
	s_waitcnt vmcnt(6)
	ds_write_b128 v193, v[6:9]
	s_waitcnt vmcnt(5)
	ds_write_b128 v192, v[10:13] offset:8192
	s_waitcnt vmcnt(4)
	ds_write_b128 v193, v[14:17] offset:8192
	s_waitcnt vmcnt(3)
	ds_write_b128 v192, v[18:21] offset:16384
	s_waitcnt vmcnt(2)
	ds_write_b128 v193, v[22:25] offset:16384
	s_waitcnt vmcnt(1)
	ds_write_b128 v192, v[26:29] offset:24576
	s_waitcnt vmcnt(0)
	ds_write_b128 v193, v[30:33] offset:24576
	s_waitcnt lgkmcnt(0)
	s_barrier
	s_add_u32 s10, s8, 0x80000
	s_addc_u32 s11, s9, 0
	s_add_u32 s12, s8, 0x100000
	s_addc_u32 s13, s9, 0
	s_add_u32 s14, s8, 0x180000
	s_addc_u32 s15, s9, 0
	s_add_u32 s16, s6, 0x7800080
	s_addc_u32 s17, s7, 0
	s_add_u32 s18, s16, 0x80000
	s_addc_u32 s19, s17, 0
	s_add_u32 s20, s16, 0x100000
	s_addc_u32 s21, s17, 0
	s_add_u32 s22, s16, 0x180000
	s_addc_u32 s23, s17, 0
	v_lshrrev_b32_e32 v170, 3, v204
	v_lshrrev_b32_e32 v171, 4, v204
	v_xor_b32_e32 v171, v171, v204
	v_and_b32_e32 v171, 7, v171
	v_lshlrev_b32_e32 v171, 4, v171
	v_lshl_or_b32 v170, v170, 13, v171
	v_readfirstlane_b32 s24, v204
	s_and_b32 s24, s24, 0x3c0
	s_lshl_b32 s24, s24, 4
	s_mov_b32 s3, 0
	ds_read_b128 v[130:133], v184
	ds_read_b128 v[138:141], v180
	ds_read_b128 v[134:137], v184 offset:4096
	ds_read_b128 v[142:145], v180 offset:4096
	ds_read_b128 v[146:149], v180 offset:8192
	ds_read_b128 v[150:153], v180 offset:12288
	s_add_u32 m0, s24, 0x8000
	s_nop 0
	global_load_lds_dwordx4 v170, s[8:9]
	s_add_u32 m0, s24, 0x18000
	s_nop 0
	global_load_lds_dwordx4 v170, s[16:17]
	s_add_u32 m0, s24, 0xa000
	s_nop 0
	global_load_lds_dwordx4 v170, s[10:11]
	s_add_u32 m0, s24, 0x1a000
	s_nop 0
	global_load_lds_dwordx4 v170, s[18:19]
	s_add_u32 m0, s24, 0xc000
	s_nop 0
	global_load_lds_dwordx4 v170, s[12:13]
	s_add_u32 m0, s24, 0x1c000
	s_nop 0
	global_load_lds_dwordx4 v170, s[20:21]
	s_add_u32 m0, s24, 0xe000
	s_nop 0
	global_load_lds_dwordx4 v170, s[14:15]
	s_add_u32 m0, s24, 0x1e000
	s_nop 0
	global_load_lds_dwordx4 v170, s[22:23]
	ds_read_b128 v[154:157], v185
	ds_read_b128 v[162:165], v181
	ds_read_b128 v[158:161], v185 offset:4096
	ds_read_b128 v[166:169], v181 offset:4096
	ds_read_b128 v[194:197], v181 offset:8192
	ds_read_b128 v[198:201], v181 offset:12288
	s_waitcnt lgkmcnt(6)
	v_mfma_f32_32x32x16_bf16 v[66:81], v[130:133], v[138:141], 0
	s_add_u32 s8, s8, 0x80
	s_addc_u32 s9, s9, 0
	v_mfma_f32_32x32x16_bf16 v[114:129], v[134:137], v[138:141], 0
	s_add_u32 s10, s10, 0x80
	s_addc_u32 s11, s11, 0
	v_mfma_f32_32x32x16_bf16 v[82:97], v[130:133], v[142:145], 0
	s_add_u32 s12, s12, 0x80
	s_addc_u32 s13, s13, 0
	v_mfma_f32_32x32x16_bf16 v[98:113], v[134:137], v[142:145], 0
	s_add_u32 s14, s14, 0x80
	s_addc_u32 s15, s15, 0
	v_mfma_f32_32x32x16_bf16 v[18:33], v[130:133], v[146:149], 0
	s_add_u32 s16, s16, 0x80
	s_addc_u32 s17, s17, 0
	v_mfma_f32_32x32x16_bf16 v[50:65], v[134:137], v[146:149], 0
	s_add_u32 s18, s18, 0x80
	s_addc_u32 s19, s19, 0
	v_mfma_f32_32x32x16_bf16 v[2:17], v[130:133], v[150:153], 0
	s_add_u32 s20, s20, 0x80
	s_addc_u32 s21, s21, 0
	v_mfma_f32_32x32x16_bf16 v[34:49], v[134:137], v[150:153], 0
	s_add_u32 s22, s22, 0x80
	s_addc_u32 s23, s23, 0
	s_branch .Lg_mlp2_mid2

.Lg_mlp2_mid2:
	ds_read_b128 v[130:133], v186
	ds_read_b128 v[138:141], v182
	ds_read_b128 v[134:137], v186 offset:4096
	ds_read_b128 v[142:145], v182 offset:4096
	ds_read_b128 v[146:149], v182 offset:8192
	ds_read_b128 v[150:153], v182 offset:12288
	s_waitcnt lgkmcnt(6)
	v_mfma_f32_32x32x16_bf16 v[66:81], v[154:157], v[162:165], v[66:81]
	v_mfma_f32_32x32x16_bf16 v[114:129], v[158:161], v[162:165], v[114:129]
	v_mfma_f32_32x32x16_bf16 v[82:97], v[154:157], v[166:169], v[82:97]
	v_mfma_f32_32x32x16_bf16 v[98:113], v[158:161], v[166:169], v[98:113]
	v_mfma_f32_32x32x16_bf16 v[18:33], v[154:157], v[194:197], v[18:33]
	v_mfma_f32_32x32x16_bf16 v[50:65], v[158:161], v[194:197], v[50:65]
	v_mfma_f32_32x32x16_bf16 v[2:17], v[154:157], v[198:201], v[2:17]
	v_mfma_f32_32x32x16_bf16 v[34:49], v[158:161], v[198:201], v[34:49]
	ds_read_b128 v[154:157], v187
	ds_read_b128 v[162:165], v183
	ds_read_b128 v[158:161], v187 offset:4096
	ds_read_b128 v[166:169], v183 offset:4096
	ds_read_b128 v[194:197], v183 offset:8192
	ds_read_b128 v[198:201], v183 offset:12288
	s_waitcnt lgkmcnt(6)
	v_mfma_f32_32x32x16_bf16 v[66:81], v[130:133], v[138:141], v[66:81]
	v_mfma_f32_32x32x16_bf16 v[114:129], v[134:137], v[138:141], v[114:129]
	v_mfma_f32_32x32x16_bf16 v[82:97], v[130:133], v[142:145], v[82:97]
	v_mfma_f32_32x32x16_bf16 v[98:113], v[134:137], v[142:145], v[98:113]
	v_mfma_f32_32x32x16_bf16 v[18:33], v[130:133], v[146:149], v[18:33]
	v_mfma_f32_32x32x16_bf16 v[50:65], v[134:137], v[146:149], v[50:65]
	v_mfma_f32_32x32x16_bf16 v[2:17], v[130:133], v[150:153], v[2:17]
	v_mfma_f32_32x32x16_bf16 v[34:49], v[134:137], v[150:153], v[34:49]
	s_waitcnt vmcnt(0) lgkmcnt(0)
	s_barrier
	ds_read_b128 v[130:133], v184 offset:32768
	ds_read_b128 v[138:141], v188
	ds_read_b128 v[134:137], v184 offset:36864
	ds_read_b128 v[142:145], v188 offset:4096
	ds_read_b128 v[146:149], v188 offset:8192
	ds_read_b128 v[150:153], v188 offset:12288
	s_cmp_ge_u32 s3, 62
	s_cbranch_scc1 .Lg_mlp2_nodma
	s_add_u32 m0, s24, 0x0
	v_mfma_f32_32x32x16_bf16 v[66:81], v[154:157], v[162:165], v[66:81]
	global_load_lds_dwordx4 v170, s[8:9]
	s_add_u32 m0, s24, 0x10000
	v_mfma_f32_32x32x16_bf16 v[114:129], v[158:161], v[162:165], v[114:129]
	global_load_lds_dwordx4 v170, s[16:17]
	s_add_u32 m0, s24, 0x2000
	v_mfma_f32_32x32x16_bf16 v[82:97], v[154:157], v[166:169], v[82:97]
	global_load_lds_dwordx4 v170, s[10:11]
	s_add_u32 m0, s24, 0x12000
	v_mfma_f32_32x32x16_bf16 v[98:113], v[158:161], v[166:169], v[98:113]
	global_load_lds_dwordx4 v170, s[18:19]
	s_add_u32 m0, s24, 0x4000
	v_mfma_f32_32x32x16_bf16 v[18:33], v[154:157], v[194:197], v[18:33]
	global_load_lds_dwordx4 v170, s[12:13]
	s_add_u32 m0, s24, 0x14000
	v_mfma_f32_32x32x16_bf16 v[50:65], v[158:161], v[194:197], v[50:65]
	global_load_lds_dwordx4 v170, s[20:21]
	s_add_u32 m0, s24, 0x6000
	v_mfma_f32_32x32x16_bf16 v[2:17], v[154:157], v[198:201], v[2:17]
	global_load_lds_dwordx4 v170, s[14:15]
	s_add_u32 m0, s24, 0x16000
	v_mfma_f32_32x32x16_bf16 v[34:49], v[158:161], v[198:201], v[34:49]
	global_load_lds_dwordx4 v170, s[22:23]
	s_branch .Lg_mlp2_join
